# hand-written weight-conversion chunk body in the w_out filler (8 loads in flight, one LDS transpose pass)
# speedup vs baseline: 1.0023x; 1.0023x over previous
; DEV int lane_id() { int l; asm volatile("v_mbcnt_lo_u32_b32 %0, -1, 0\n\tv_mbcnt_hi_u32_b32 %0, -1, %0" : "=v"(l)); return l; }
; #define KPTR(T, ap64, i) ((T*)(__attribute__((address_space(1))) T*)(ap64)[i])
; template <class AP> DEV CvtMat cvt_mat_of(int L, int t, unsigned char* ws, AP ap) {
;     unsigned char* wl = ws + WS_W + (size_t)L * WL_SIZE; CvtMat m;
;     if (t < 384) { m = CvtMat{KPTR(const float, ap, 9) + (size_t)L * DM * DIN, nullptr, KPTR(const float, ap, 8) + L * DM, (bf16_t*)(wl + WL_IN), CV_WIN, DINP, DM, 0, t}; }
;     else if (t < 432) { m = CvtMat{KPTR(const float, ap, 21) + (size_t)L * 256 * 768, nullptr, KPTR(const float, ap, 20) + L * 256, (bf16_t*)(wl + WL_QB), CV_WQB, 768, 256, 0, t - 384}; }
;     else if (t < 496) { m = CvtMat{KPTR(const float, ap, 23) + (size_t)L * 128 * 512, KPTR(const float, ap, 24) + (size_t)L * 128 * 512, KPTR(const float, ap, 22) + L * 128, (bf16_t*)(wl + WL_KV), CV_WKV, 1024, 256, 0, t - 432}; }
;     else if (t < 512) { m = CvtMat{KPTR(const float, ap, 18) + (size_t)L * 65536, nullptr, nullptr, (bf16_t*)(wl + WL_GLU), CV_T, 256, 256, 256, t - 496}; }
;     else if (t < 768) { m = CvtMat{KPTR(const float, ap, 28) + (size_t)L * DM * DM, nullptr, nullptr, (bf16_t*)(wl + WL_OUT), CV_T, DM, DM, DM, t - 512}; }
;     else if (t < 2176) { m = CvtMat{KPTR(const float, ap, 30) + (size_t)L * DM * DFF2, nullptr, KPTR(const float, ap, 29) + L * DM, (bf16_t*)(wl + WL_FFI), CV_WFFI, DFF2, DM, 0, t - 768}; }
;     else { m = CvtMat{KPTR(const float, ap, 33) + (size_t)L * DFF * DM, nullptr, nullptr, (bf16_t*)(wl + WL_FFO), CV_T, DM, DFF, DM, t - 2176}; }
;     return m;
; __global__ void __launch_bounds__(512, 2) mk_fwd(MKArgs args) {
;     ...
;               for (;;) {
;                   if (wave_s == 0 && lane_id() == 0) LQ[1] = __hip_atomic_fetch_add(qc, 1u, __ATOMIC_RELAXED, __HIP_MEMORY_SCOPE_AGENT);
;                   __syncthreads(); const unsigned idx = LQ[1]; __syncthreads();
;                   if (idx >= NC) break;
;                   { PHASE_IDS const int tb_ = CVT_Q0 + CVT_CH * (int)idx; cvt_layer_wg(l + 1, 0, 1, tid, ldsl + RING_OFF, ws, ap, tb_, tb_ + CVT_CH < CVT_TILES_PER_LAYER ? tb_ + CVT_CH : CVT_TILES_PER_LAYER); }
.LBB0_1637:
	v_mov_b32_e32 v0, s33
	s_waitcnt lgkmcnt(0)
	s_barrier
	ds_read_b32 v0, v0
	s_movk_i32 s6, 0x2cf
	s_waitcnt lgkmcnt(0)
	s_barrier
	v_cmp_lt_u32_e32 vcc, s6, v0
	v_readfirstlane_b32 s48, v0
	s_cbranch_vccnz .LBB0_1907
	v_readlane_b32 s49, v255, 16
	s_cmpk_lt_u32 s48, 0x60
	s_cselect_b64 s[50:51], -1, 0
	s_movk_i32 s62, 0x100
	s_mov_b32 s64, 0
	s_mov_b32 s65, 0
	s_mov_b32 s70, 0
	s_mov_b32 s7, 0
	s_movk_i32 s71, 0x7fff
	s_mov_b32 s72, 0
	s_cmpk_lt_u32 s48, 0x60
	s_cbranch_scc1 .Lcvf_win
	s_cmpk_lt_u32 s48, 0x6c
	s_cbranch_scc1 .Lcvf_wqb
	s_cmpk_lt_u32 s48, 0x7c
	s_cbranch_scc1 .Lcvf_wkv
	s_cmpk_lt_u32 s48, 0x80
	s_cbranch_scc1 .Lcvf_glu
	s_cmpk_lt_u32 s48, 0xc0
	s_cbranch_scc1 .Lcvf_wout
	s_cmpk_lt_u32 s48, 0x220
	s_cbranch_scc1 .Lcvf_ffi
	s_add_i32 s6, s48, 0xfffffde0
	s_lshr_b32 s73, s6, 2
	s_and_b32 s6, s6, 3
	s_load_dwordx2 s[14:15], s[2:3], 0x108
	s_mul_i32 s10, s49, 0xb00000
	s_movk_i32 s56, 0x1000
	s_movk_i32 s60, 0x1600
	s_mov_b64 s[58:59], s[28:29]
	s_lshl_b32 s63, s6, 10
	s_waitcnt lgkmcnt(0)
	s_add_u32 s52, s14, s10
	s_addc_u32 s53, s15, 0
	s_branch .Lcvf_common
.Lcvf_win:
	s_mul_hi_u32 s73, s48, 0xaaaaaaab
	s_lshr_b32 s73, s73, 2
	s_mul_i32 s6, s73, 6
	s_sub_u32 s6, s48, s6
	s_load_dwordx4 s[12:15], s[2:3], 0x40
	s_mul_i32 s10, s49, 0x5b0000
	s_lshl_b32 s11, s49, 12
	s_movk_i32 s56, 0x16c0
	s_movk_i32 s60, 0x800
	s_mov_b64 s[58:59], s[26:27]
	s_mov_b32 s72, 1
	s_lshl_b32 s63, s6, 10
	s_cmp_lt_u32 s6, 3
	s_cbranch_scc1 .Lcvf_win_a
	s_add_i32 s63, s63, 0xfffffe80
.Lcvf_win_a:
	s_cmp_lg_u32 s6, 5
	s_cbranch_scc1 .Lcvf_win_c
	s_add_i32 s63, s63, 64
.Lcvf_win_c:
	s_cmp_lg_u32 s6, 2
	s_cbranch_scc1 .Lcvf_win_b
	s_movk_i32 s62, 0xa0
	s_movk_i32 s64, 0xb0
	s_movk_i32 s65, 0x1000
.Lcvf_win_b:
	s_waitcnt lgkmcnt(0)
	s_add_u32 s52, s14, s10
	s_addc_u32 s53, s15, 0
	s_add_u32 s54, s12, s11
	s_addc_u32 s55, s13, 0
	s_branch .Lcvf_common
.Lcvf_wqb:
	s_add_i32 s6, s48, 0xffffffa0
	s_mul_hi_u32 s73, s6, 0xaaaaaaab
	s_lshr_b32 s73, s73, 1
	s_mul_i32 s10, s73, 3
	s_sub_u32 s6, s6, s10
	s_load_dwordx4 s[12:15], s[2:3], 0xa0
	s_mul_i32 s10, s49, 0xc0000
	s_lshl_b32 s11, s49, 10
	s_movk_i32 s56, 0xc00
	s_movk_i32 s60, 0x200
	s_mov_b64 s[58:59], s[46:47]
	s_mov_b32 s72, 1
	s_mul_i32 s63, s6, 0x600
	s_movk_i32 s70, 0x80
	s_cmp_lg_u32 s6, 2
	s_cbranch_scc1 .Lcvf_wqb_a
	s_mov_b32 s72, 3
	s_movk_i32 s70, 0x200
	s_mov_b32 s7, 48

; DEV f32x4 cvt_src4(int kind, const float* src, const float* src2, const float* gain, int ld, int k, int n) {
;     f32x4 v = (f32x4){0.f, 0.f, 0.f, 0.f}; float g = 1.f;
;     if (kind == CV_WIN) { const int c = colmap_win(n); if (c >= 0) { v = *(const f32x4*)(src + (size_t)k * DIN + c); g = gain[k]; } }
;     else if (kind == CV_WQB) { v = *(const f32x4*)(src + (size_t)k * 768 + colmap_qb(n)); g = gain[k]; }
;     else if (kind == CV_WKV) { if (k < 128) { const int nn = n & 511; v = *(const f32x4*)((n < 512 ? src : src2) + ((size_t)k * 8 + (nn >> 6)) * 64 + (nn & 63)); g = gain[k]; } }
;     else if (kind == CV_T) v = *(const f32x4*)(src + (size_t)k * ld + n);
;     else { v = *(const f32x4*)(src + (size_t)k * DFF2 + colmap_ffi(n)); g = gain[k]; }
;     return v * g;
; }
;     ...
;     if (t < t_end) { const CvtMat m = cvt_mat_of(L, t, ws, ap); const int nb = m.N / 64, k0 = 64 * (m.tm / nb), n0 = 64 * (m.tm % nb);
;         c0 = cvt_src4(m.kind, m.src, m.src2, m.gain, m.ld, k0 + kk, n0 + 8 * nq); c1 = cvt_src4(m.kind, m.src, m.src2, m.gain, m.ld, k0 + kk, n0 + 8 * nq + 4); }
;     for (; t < t_end; t += nwg) {
;         const CvtMat m = cvt_mat_of(L, t, ws, ap); const int nb = m.N / 64, k0 = 64 * (m.tm / nb), n0 = 64 * (m.tm % nb);
.Lcvf_wkv:
	s_add_i32 s6, s48, 0xffffff94
	s_lshr_b32 s73, s6, 2
	s_and_b32 s6, s6, 3
	s_load_dwordx4 s[12:15], s[2:3], 0xb0
	s_load_dwordx2 s[10:11], s[2:3], 0xc0
	s_lshl_b32 s80, s49, 18
	s_lshl_b32 s81, s49, 9
	s_movk_i32 s56, 0x800
	s_movk_i32 s60, 0x200
	s_mov_b64 s[58:59], s[44:45]
	s_mov_b32 s72, 1
	s_movk_i32 s71, 0x80
	s_and_b32 s63, s6, 1
	s_lshl_b32 s63, s63, 10
	s_waitcnt lgkmcnt(0)
	s_cmp_lt_u32 s6, 2
	s_cselect_b32 s14, s14, s10
	s_cselect_b32 s15, s15, s11
	s_add_u32 s52, s14, s80
	s_addc_u32 s53, s15, 0
	s_add_u32 s54, s12, s81
	s_addc_u32 s55, s13, 0
	s_branch .Lcvf_common
.Lcvf_glu:
	s_add_i32 s73, s48, 0xffffff84
	s_mov_b32 s6, 0
	s_load_dwordx2 s[14:15], s[2:3], 0x90
	s_lshl_b32 s10, s49, 18
	s_movk_i32 s56, 0x400
	s_movk_i32 s60, 0x200
	s_mov_b64 s[58:59], s[42:43]
	s_mov_b32 s63, 0
	s_waitcnt lgkmcnt(0)
	s_add_u32 s52, s14, s10
	s_addc_u32 s53, s15, 0
	s_branch .Lcvf_common
.Lcvf_wout:
	s_add_i32 s6, s48, 0xffffff80
	s_lshr_b32 s73, s6, 2
	s_and_b32 s6, s6, 3
	s_load_dwordx2 s[14:15], s[2:3], 0xe0
	s_lshl_b32 s10, s49, 22
	s_movk_i32 s56, 0x1000
	s_movk_i32 s60, 0x800
	s_mov_b64 s[58:59], s[40:41]
	s_lshl_b32 s63, s6, 10
	s_waitcnt lgkmcnt(0)
	s_add_u32 s52, s14, s10
	s_addc_u32 s53, s15, 0
	s_branch .Lcvf_common
.Lcvf_ffi:
	s_add_i32 s6, s48, 0xffffff40
	s_mul_hi_u32 s73, s6, 0xba2e8ba3
	s_lshr_b32 s73, s73, 4
	s_mul_i32 s10, s73, 22
	s_sub_u32 s6, s6, s10
	s_load_dwordx4 s[12:15], s[2:3], 0xe8
	s_mul_i32 s10, s49, 0x1600000
	s_lshl_b32 s11, s49, 12
	s_movk_i32 s56, 0x5800
	s_movk_i32 s60, 0x800
	s_mov_b64 s[58:59], s[38:39]
	s_mov_b32 s72, 1
	s_movk_i32 s62, 0x80
	s_movk_i32 s64, 0x100
	s_lshl_b32 s63, s6, 9
	s_add_i32 s65, s63, 0x2a00
	s_waitcnt lgkmcnt(0)
	s_add_u32 s52, s14, s10
	s_addc_u32 s53, s15, 0
	s_add_u32 s54, s12, s11
	s_addc_u32 s55, s13, 0
.Lcvf_common:
	s_lshl_b32 s61, s73, 6
	s_mul_i32 s14, s6, s60
	s_lshl_b32 s14, s14, 8
	s_lshl_b32 s15, s61, 1
	s_add_u32 s14, s14, s15
	s_add_u32 s58, s58, s14
	s_addc_u32 s59, s59, 0
	v_mbcnt_lo_u32_b32 v2, -1, 0
	v_mbcnt_hi_u32_b32 v2, -1, v2
	v_readlane_b32 s14, v254, 3
	s_nop 1
	v_add_u32_e32 v2, s14, v2
	v_lshrrev_b32_e32 v3, 3, v2
	v_and_b32_e32 v4, 7, v2
	v_add_u32_e32 v5, s61, v3
	v_mul_lo_u32 v6, v5, s56
	v_lshlrev_b32_e32 v17, 2, v5
	v_cmp_gt_u32_e64 s[78:79], s71, v5
	v_lshlrev_b32_e32 v7, 3, v4
	v_lshlrev_b32_e32 v18, 1, v3
	v_lshlrev_b32_e32 v5, 4, v4
	v_xor_b32_e32 v18, v18, v5
	v_lshl_add_u32 v18, v4, 10, v18
	v_lshrrev_b32_e32 v5, 3, v3
	v_xor_b32_e32 v5, v5, v4
	v_lshlrev_b32_e32 v19, 7, v3
	v_lshl_add_u32 v19, v5, 4, v19
	v_mul_lo_u32 v20, v3, s60
	v_lshl_add_u32 v20, v4, 4, v20
	v_mov_b32_e32 v128, s63
	v_mov_b32_e32 v129, s65
	s_bitcmp1_b32 s72, 1
	s_cbranch_scc0 .Lcvf_norope
	v_lshrrev_b32_e32 v5, 2, v4
	v_and_b32_e32 v21, 3, v4
	v_mul_u32_u24_e32 v5, 0x180, v5
	v_lshl_add_u32 v5, v21, 4, v5
	v_lshlrev_b32_e32 v21, 5, v4
	v_sub_u32_e32 v5, v5, v21
	v_add_u32_e32 v128, 0x100, v5
.Lcvf_norope:
	v_mov_b32_e32 v16, 1.0
	s_bitcmp1_b32 s72, 0
	s_cbranch_scc0 .Lcvf_nogain
	s_and_saveexec_b64 s[10:11], s[78:79]
	s_cbranch_execz .Lcvf_gskip
	global_load_dword v16, v17, s[54:55]

; DEV f32x4 cvt_src4(int kind, const float* src, const float* src2, const float* gain, int ld, int k, int n) {
;     f32x4 v = (f32x4){0.f, 0.f, 0.f, 0.f}; float g = 1.f;
;     if (kind == CV_WIN) { const int c = colmap_win(n); if (c >= 0) { v = *(const f32x4*)(src + (size_t)k * DIN + c); g = gain[k]; } }
;     else if (kind == CV_WQB) { v = *(const f32x4*)(src + (size_t)k * 768 + colmap_qb(n)); g = gain[k]; }
;     else if (kind == CV_WKV) { if (k < 128) { const int nn = n & 511; v = *(const f32x4*)((n < 512 ? src : src2) + ((size_t)k * 8 + (nn >> 6)) * 64 + (nn & 63)); g = gain[k]; } }
;     else if (kind == CV_T) v = *(const f32x4*)(src + (size_t)k * ld + n);
;     else { v = *(const f32x4*)(src + (size_t)k * DFF2 + colmap_ffi(n)); g = gain[k]; }
;     return v * g;
; }
;     ...
;         c0 = cvt_src4(m.kind, m.src, m.src2, m.gain, m.ld, k0 + kk, n0 + 8 * nq); c1 = cvt_src4(m.kind, m.src, m.src2, m.gain, m.ld, k0 + kk, n0 + 8 * nq + 4); }
.Lcvf_nogain:
	s_mov_b32 s14, 0
	v_add_u32_e32 v5, 0, v7
	v_cmp_gt_u32_e32 vcc, s62, v5
	v_cmp_gt_u32_e64 s[80:81], s64, v5
	v_mov_b32_e32 v80, 0
	v_mov_b32_e32 v81, 0
	v_cndmask_b32_e32 v21, v129, v128, vcc
	s_or_b64 s[80:81], s[80:81], vcc
	s_and_b64 s[80:81], s[80:81], s[78:79]
	v_lshl_add_u32 v21, v5, 2, v21
	v_add3_u32 v8, v21, v6, s14
	v_mov_b32_e32 v82, 0
	v_mov_b32_e32 v83, 0
	s_and_saveexec_b64 s[10:11], s[80:81]
	s_cbranch_execz .Lcvf_ls00
	global_load_dwordx4 v[80:83], v8, s[52:53]
.Lcvf_ls00:
	s_or_b64 exec, exec, s[10:11]
	v_add_u32_e32 v5, 4, v7
	v_cmp_gt_u32_e32 vcc, s62, v5
	v_cmp_gt_u32_e64 s[80:81], s64, v5
	v_mov_b32_e32 v84, 0
	v_mov_b32_e32 v85, 0
	v_cndmask_b32_e32 v21, v129, v128, vcc
	s_or_b64 s[80:81], s[80:81], vcc
	s_and_b64 s[80:81], s[80:81], s[78:79]
	v_lshl_add_u32 v21, v5, 2, v21
	v_add_u32_e32 v21, s7, v21
	v_add3_u32 v9, v21, v6, s14
	v_mov_b32_e32 v86, 0
	v_mov_b32_e32 v87, 0
	s_and_saveexec_b64 s[10:11], s[80:81]
	s_cbranch_execz .Lcvf_ls01
	global_load_dwordx4 v[84:87], v9, s[52:53]
.Lcvf_ls01:
	s_or_b64 exec, exec, s[10:11]
	s_add_u32 s14, s14, s70
	v_add_u32_e32 v5, 64, v7
	v_cmp_gt_u32_e32 vcc, s62, v5
	v_cmp_gt_u32_e64 s[80:81], s64, v5
	v_mov_b32_e32 v88, 0
	v_mov_b32_e32 v89, 0
	v_cndmask_b32_e32 v21, v129, v128, vcc
	s_or_b64 s[80:81], s[80:81], vcc
	s_and_b64 s[80:81], s[80:81], s[78:79]
	v_lshl_add_u32 v21, v5, 2, v21
	v_add3_u32 v10, v21, v6, s14
	v_mov_b32_e32 v90, 0
	v_mov_b32_e32 v91, 0
	s_and_saveexec_b64 s[10:11], s[80:81]
	s_cbranch_execz .Lcvf_ls10
	global_load_dwordx4 v[88:91], v10, s[52:53]
.Lcvf_ls10:
	s_or_b64 exec, exec, s[10:11]
	v_add_u32_e32 v5, 68, v7
	v_cmp_gt_u32_e32 vcc, s62, v5
	v_cmp_gt_u32_e64 s[80:81], s64, v5
	v_mov_b32_e32 v92, 0
	v_mov_b32_e32 v93, 0
	v_cndmask_b32_e32 v21, v129, v128, vcc
	s_or_b64 s[80:81], s[80:81], vcc
	s_and_b64 s[80:81], s[80:81], s[78:79]
	v_lshl_add_u32 v21, v5, 2, v21
	v_add_u32_e32 v21, s7, v21
	v_add3_u32 v11, v21, v6, s14
	v_mov_b32_e32 v94, 0
	v_mov_b32_e32 v95, 0
	s_and_saveexec_b64 s[10:11], s[80:81]
	s_cbranch_execz .Lcvf_ls11
	global_load_dwordx4 v[92:95], v11, s[52:53]
.Lcvf_ls11:
	s_or_b64 exec, exec, s[10:11]
	s_add_u32 s14, s14, s70
	v_add_u32_e32 v5, 128, v7
	v_cmp_gt_u32_e32 vcc, s62, v5
	v_cmp_gt_u32_e64 s[80:81], s64, v5
	v_mov_b32_e32 v96, 0
	v_mov_b32_e32 v97, 0
	v_cndmask_b32_e32 v21, v129, v128, vcc
	s_or_b64 s[80:81], s[80:81], vcc
	s_and_b64 s[80:81], s[80:81], s[78:79]
	v_lshl_add_u32 v21, v5, 2, v21
	v_add3_u32 v12, v21, v6, s14
	v_mov_b32_e32 v98, 0
	v_mov_b32_e32 v99, 0
	s_and_saveexec_b64 s[10:11], s[80:81]
	s_cbranch_execz .Lcvf_ls20
	global_load_dwordx4 v[96:99], v12, s[52:53]
.Lcvf_ls20:
	s_or_b64 exec, exec, s[10:11]
	v_add_u32_e32 v5, 132, v7
	v_cmp_gt_u32_e32 vcc, s62, v5
	v_cmp_gt_u32_e64 s[80:81], s64, v5
	v_mov_b32_e32 v100, 0
	v_mov_b32_e32 v101, 0
	v_cndmask_b32_e32 v21, v129, v128, vcc
	s_or_b64 s[80:81], s[80:81], vcc
	s_and_b64 s[80:81], s[80:81], s[78:79]
	v_lshl_add_u32 v21, v5, 2, v21
	v_add_u32_e32 v21, s7, v21
	v_add3_u32 v13, v21, v6, s14
	v_mov_b32_e32 v102, 0
	v_mov_b32_e32 v103, 0
	s_and_saveexec_b64 s[10:11], s[80:81]
	s_cbranch_execz .Lcvf_ls21
	global_load_dwordx4 v[100:103], v13, s[52:53]
.Lcvf_ls21:
	s_or_b64 exec, exec, s[10:11]
	s_add_u32 s14, s14, s70
	v_add_u32_e32 v5, 192, v7
	v_cmp_gt_u32_e32 vcc, s62, v5
	v_cmp_gt_u32_e64 s[80:81], s64, v5
	v_mov_b32_e32 v104, 0
	v_mov_b32_e32 v105, 0
	v_cndmask_b32_e32 v21, v129, v128, vcc
	s_or_b64 s[80:81], s[80:81], vcc
	s_and_b64 s[80:81], s[80:81], s[78:79]
	v_lshl_add_u32 v21, v5, 2, v21
	v_add3_u32 v14, v21, v6, s14
	v_mov_b32_e32 v106, 0
	v_mov_b32_e32 v107, 0
	s_and_saveexec_b64 s[10:11], s[80:81]
	s_cbranch_execz .Lcvf_ls30
	global_load_dwordx4 v[104:107], v14, s[52:53]
; DEV bf16_t f2bf(float f) { unsigned u = __float_as_uint(f); u += 0x7fffu + ((u >> 16) & 1u); return (bf16_t)(u >> 16); }
; DEV void lds_barrier() { asm volatile("s_waitcnt lgkmcnt(0)" ::: "memory"); __builtin_amdgcn_s_barrier(); asm volatile("" ::: "memory"); }
; #define LAS __attribute__((address_space(3)))
;     ...
;         for (int e = 0; e < 4; ++e) { T[(8 * nq + e) * 72 + kk] = f2bf(c0[e]); T[(8 * nq + 4 + e) * 72 + kk] = f2bf(c1[e]); }
;         if (t + nwg < t_end) { const CvtMat m2 = cvt_mat_of(L, t + nwg, ws, ap); const int nb2 = m2.N / 64, k2 = 64 * (m2.tm / nb2), n2 = 64 * (m2.tm % nb2);
;             c0 = cvt_src4(m2.kind, m2.src, m2.src2, m2.gain, m2.ld, k2 + kk, n2 + 8 * nq); c1 = cvt_src4(m2.kind, m2.src, m2.src2, m2.gain, m2.ld, k2 + kk, n2 + 8 * nq + 4); }
;         lds_barrier();
;         { const int nl = tid >> 3, kc = tid & 7; *(u32x4*)(m.dst + (size_t)(n0 + nl) * m.K + k0 + 8 * kc) = *(const LAS u32x4*)(T + nl * 72 + 8 * kc); }
.Lcvf_ls30:
	s_or_b64 exec, exec, s[10:11]
	v_add_u32_e32 v5, 196, v7
	v_cmp_gt_u32_e32 vcc, s62, v5
	v_cmp_gt_u32_e64 s[80:81], s64, v5
	v_mov_b32_e32 v108, 0
	v_mov_b32_e32 v109, 0
	v_cndmask_b32_e32 v21, v129, v128, vcc
	s_or_b64 s[80:81], s[80:81], vcc
	s_and_b64 s[80:81], s[80:81], s[78:79]
	v_lshl_add_u32 v21, v5, 2, v21
	v_add_u32_e32 v21, s7, v21
	v_add3_u32 v15, v21, v6, s14
	v_mov_b32_e32 v110, 0
	v_mov_b32_e32 v111, 0
	s_and_saveexec_b64 s[10:11], s[80:81]
	s_cbranch_execz .Lcvf_ls31
	global_load_dwordx4 v[108:111], v15, s[52:53]
.Lcvf_ls31:
	s_or_b64 exec, exec, s[10:11]
	s_waitcnt vmcnt(0)
	v_mul_f32_e32 v112, v16, v80
	v_mul_f32_e32 v113, v16, v81
	v_mul_f32_e32 v114, v16, v82
	v_mul_f32_e32 v115, v16, v83
	v_cvt_pk_bf16_f32 v116, v112, v113
	v_cvt_pk_bf16_f32 v117, v114, v115
	ds_write_b16 v18, v116 offset:0
	ds_write_b16_d16_hi v18, v116 offset:128
	ds_write_b16 v18, v117 offset:256
	ds_write_b16_d16_hi v18, v117 offset:384
	v_mul_f32_e32 v112, v16, v84
	v_mul_f32_e32 v113, v16, v85
	v_mul_f32_e32 v114, v16, v86
	v_mul_f32_e32 v115, v16, v87
	v_cvt_pk_bf16_f32 v116, v112, v113
	v_cvt_pk_bf16_f32 v117, v114, v115
	ds_write_b16 v18, v116 offset:512
	ds_write_b16_d16_hi v18, v116 offset:640
	ds_write_b16 v18, v117 offset:768
	ds_write_b16_d16_hi v18, v117 offset:896
	v_mul_f32_e32 v112, v16, v88
	v_mul_f32_e32 v113, v16, v89
	v_mul_f32_e32 v114, v16, v90
	v_mul_f32_e32 v115, v16, v91
	v_cvt_pk_bf16_f32 v116, v112, v113
	v_cvt_pk_bf16_f32 v117, v114, v115
	ds_write_b16 v18, v116 offset:8192
	ds_write_b16_d16_hi v18, v116 offset:8320
	ds_write_b16 v18, v117 offset:8448
	ds_write_b16_d16_hi v18, v117 offset:8576
	v_mul_f32_e32 v112, v16, v92
	v_mul_f32_e32 v113, v16, v93
	v_mul_f32_e32 v114, v16, v94
	v_mul_f32_e32 v115, v16, v95
	v_cvt_pk_bf16_f32 v116, v112, v113
	v_cvt_pk_bf16_f32 v117, v114, v115
	ds_write_b16 v18, v116 offset:8704
	ds_write_b16_d16_hi v18, v116 offset:8832
	ds_write_b16 v18, v117 offset:8960
	ds_write_b16_d16_hi v18, v117 offset:9088
	v_mul_f32_e32 v112, v16, v96
	v_mul_f32_e32 v113, v16, v97
	v_mul_f32_e32 v114, v16, v98
	v_mul_f32_e32 v115, v16, v99
	v_cvt_pk_bf16_f32 v116, v112, v113
	v_cvt_pk_bf16_f32 v117, v114, v115
	ds_write_b16 v18, v116 offset:16384
	ds_write_b16_d16_hi v18, v116 offset:16512
	ds_write_b16 v18, v117 offset:16640
	ds_write_b16_d16_hi v18, v117 offset:16768
	v_mul_f32_e32 v112, v16, v100
	v_mul_f32_e32 v113, v16, v101
	v_mul_f32_e32 v114, v16, v102
	v_mul_f32_e32 v115, v16, v103
	v_cvt_pk_bf16_f32 v116, v112, v113
	v_cvt_pk_bf16_f32 v117, v114, v115
	ds_write_b16 v18, v116 offset:16896
	ds_write_b16_d16_hi v18, v116 offset:17024
	ds_write_b16 v18, v117 offset:17152
	ds_write_b16_d16_hi v18, v117 offset:17280
	v_mul_f32_e32 v112, v16, v104
	v_mul_f32_e32 v113, v16, v105
	v_mul_f32_e32 v114, v16, v106
	v_mul_f32_e32 v115, v16, v107
	v_cvt_pk_bf16_f32 v116, v112, v113
	v_cvt_pk_bf16_f32 v117, v114, v115
	ds_write_b16 v18, v116 offset:24576
	ds_write_b16_d16_hi v18, v116 offset:24704
	ds_write_b16 v18, v117 offset:24832
	ds_write_b16_d16_hi v18, v117 offset:24960
	v_mul_f32_e32 v112, v16, v108
	v_mul_f32_e32 v113, v16, v109
	v_mul_f32_e32 v114, v16, v110
	v_mul_f32_e32 v115, v16, v111
	v_cvt_pk_bf16_f32 v116, v112, v113
	v_cvt_pk_bf16_f32 v117, v114, v115
	ds_write_b16 v18, v116 offset:25088
	ds_write_b16_d16_hi v18, v116 offset:25216
	ds_write_b16 v18, v117 offset:25344
	ds_write_b16_d16_hi v18, v117 offset:25472
	s_waitcnt lgkmcnt(0)
	s_barrier
	ds_read_b128 v[80:83], v19 offset:0
	ds_read_b128 v[84:87], v19 offset:8192
	ds_read_b128 v[88:91], v19 offset:16384
	ds_read_b128 v[92:95], v19 offset:24576
	s_lshl_b32 s14, s60, 6
	s_mov_b64 s[12:13], s[58:59]
	s_waitcnt lgkmcnt(3)
	global_store_dwordx4 v20, v[80:83], s[12:13]
	s_add_u32 s12, s12, s14
	s_addc_u32 s13, s13, 0
	s_waitcnt lgkmcnt(2)
	global_store_dwordx4 v20, v[84:87], s[12:13]
	s_add_u32 s12, s12, s14
	s_addc_u32 s13, s13, 0
	s_waitcnt lgkmcnt(1)
	global_store_dwordx4 v20, v[88:91], s[12:13]
	s_add_u32 s12, s12, s14
	s_addc_u32 s13, s13, 0
	s_waitcnt lgkmcnt(0)
	global_store_dwordx4 v20, v[92:95], s[12:13]
	s_waitcnt vmcnt(0)
	s_branch .LBB0_1908

; DEV void wg_post(unsigned* c, int wave_s) { __syncthreads(); if (wave_s == 0 && lane_id() == 0) { __builtin_amdgcn_fence(__ATOMIC_RELEASE, "agent"); asm volatile("s_waitcnt vmcnt(0)" ::: "memory"); __hip_atomic_fetch_add(c, 1u, __ATOMIC_RELAXED, __HIP_MEMORY_SCOPE_AGENT); } }
; __global__ void __launch_bounds__(512, 2) mk_fwd(MKArgs args) {
;     ...
;                   __syncthreads(); const unsigned idx = LQ[1]; __syncthreads();
;                   if (idx >= NC) break;
;                   { PHASE_IDS const int tb_ = CVT_Q0 + CVT_CH * (int)idx; cvt_layer_wg(l + 1, 0, 1, tid, ldsl + RING_OFF, ws, ap, tb_, tb_ + CVT_CH < CVT_TILES_PER_LAYER ? tb_ + CVT_CH : CVT_TILES_PER_LAYER); }
;                   if (mrg && CVT_CH * (idx + 1) <= 384u) wg_post(ctl + CW_WIN + 64 * (l + 1), wave_s); } }
.LBB0_1908:
	s_waitcnt lgkmcnt(0)
	s_barrier
	s_and_b64 s[6:7], s[0:1], s[50:51]
	s_mov_b64 s[50:51], -1
	s_andn2_b64 vcc, exec, s[6:7]
	s_mov_b64 s[54:55], -1
	s_cbranch_vccnz .LBB0_1636
	v_readlane_b32 s54, v254, 4
	s_mov_b64 s[50:51], 0
	v_readlane_b32 s55, v254, 5
	s_barrier
	s_branch .LBB0_1636
.LBB0_1911:
	s_xor_b64 s[6:7], s[52:53], -1
	s_andn2_b64 vcc, exec, s[6:7]
	s_mov_b64 s[52:53], -1
	s_cbranch_vccnz .LBB0_1629
	s_xor_b64 s[6:7], s[50:51], -1
	s_and_b64 vcc, exec, s[6:7]
	s_cbranch_vccz .LBB0_1628
	v_mbcnt_lo_u32_b32 v0, -1, 0
	v_mbcnt_hi_u32_b32 v0, -1, v0
	s_nop 0
	v_cmp_eq_u32_e32 vcc, 0, v0
	s_and_saveexec_b64 s[6:7], vcc
	s_xor_b64 s[50:51], exec, s[6:7]
	s_cbranch_execz .LBB0_1627
	s_mov_b64 s[52:53], exec
	buffer_wbl2 sc1
	s_waitcnt vmcnt(0)
	s_waitcnt vmcnt(0)
	v_mbcnt_lo_u32_b32 v0, s52, 0
	v_mbcnt_hi_u32_b32 v0, s53, v0
	v_cmp_eq_u32_e32 vcc, 0, v0
	s_and_saveexec_b64 s[6:7], vcc
	s_xor_b64 s[54:55], exec, s[6:7]
	s_cbranch_execz .LBB0_1626
	s_bcnt1_i32_b64 s6, s[52:53]
	v_mov_b32_e32 v0, s6
	v_readlane_b32 s6, v254, 58
	v_readlane_b32 s7, v254, 59
	s_nop 4
	global_atomic_add v1, v0, s[6:7]
	s_branch .LBB0_1626
